# HGRN pass-B loop: 4 steps per iteration (one pointer update per step), half-mirror add fused into the DPP op
# baseline (speedup 1.0000x reference)
.Lhg_loop:
	s_waitcnt lgkmcnt(3)
	ds_read_b128 v[60:63], v113 offset:512
	ds_read_b128 v[56:59], v113 offset:528
	ds_read_b32 v88, v114 offset:512
	v_pk_mul_f32 v[108:109], v[52:53], v[86:87]
	v_pk_add_f32 v[92:93], v[86:87], v[90:91] op_sel_hi:[1,0] neg_lo:[0,1] neg_hi:[0,1]
	v_pk_add_f32 v[94:95], v[84:85], v[90:91] op_sel_hi:[1,0] neg_lo:[0,1] neg_hi:[0,1]
	v_pk_fma_f32 v[108:109], v[54:55], v[84:85], v[108:109]
	v_pk_add_f32 v[104:105], v[82:83], v[90:91] op_sel_hi:[1,0] neg_lo:[0,1] neg_hi:[0,1]
	v_pk_add_f32 v[106:107], v[80:81], v[90:91] op_sel_hi:[1,0] neg_lo:[0,1] neg_hi:[0,1]
	v_pk_fma_f32 v[108:109], v[48:49], v[82:83], v[108:109]
	v_pk_fma_f32 v[86:87], v[64:65], v[92:93], v[90:91] op_sel_hi:[1,1,0]
	v_pk_fma_f32 v[84:85], v[66:67], v[94:95], v[90:91] op_sel_hi:[1,1,0]
	v_pk_fma_f32 v[108:109], v[50:51], v[80:81], v[108:109]
	ds_read_b128 v[52:55], v115 offset:512
	ds_read_b128 v[48:51], v115 offset:528
	v_add_f32_e32 v110, v108, v109
	v_pk_fma_f32 v[82:83], v[68:69], v[104:105], v[90:91] op_sel_hi:[1,1,0]
	v_pk_fma_f32 v[80:81], v[70:71], v[106:107], v[90:91] op_sel_hi:[1,1,0]
	v_add_f32_dpp v110, v110, v110 quad_perm:[1,0,3,2] row_mask:0xf bank_mask:0xf bound_ctrl:1
	s_nop 1
	v_add_f32_dpp v110, v110, v110 quad_perm:[2,3,0,1] row_mask:0xf bank_mask:0xf bound_ctrl:1
	s_nop 1
	v_add_f32_dpp v110, v110, v110 row_half_mirror row_mask:0xf bank_mask:0xf bound_ctrl:1
	s_nop 0
	ds_write_b32 v112, v110
	s_waitcnt lgkmcnt(3)
	ds_read_b128 v[64:67], v113 offset:768
	ds_read_b128 v[68:71], v113 offset:784
	ds_read_b32 v90, v114 offset:768
	v_pk_mul_f32 v[108:109], v[72:73], v[86:87]
	v_pk_add_f32 v[92:93], v[86:87], v[88:89] op_sel_hi:[1,0] neg_lo:[0,1] neg_hi:[0,1]
	v_pk_add_f32 v[94:95], v[84:85], v[88:89] op_sel_hi:[1,0] neg_lo:[0,1] neg_hi:[0,1]
	v_pk_fma_f32 v[108:109], v[74:75], v[84:85], v[108:109]
	v_pk_add_f32 v[104:105], v[82:83], v[88:89] op_sel_hi:[1,0] neg_lo:[0,1] neg_hi:[0,1]
	v_pk_add_f32 v[106:107], v[80:81], v[88:89] op_sel_hi:[1,0] neg_lo:[0,1] neg_hi:[0,1]
	v_pk_fma_f32 v[108:109], v[76:77], v[82:83], v[108:109]
	v_pk_fma_f32 v[86:87], v[60:61], v[92:93], v[88:89] op_sel_hi:[1,1,0]
	v_pk_fma_f32 v[84:85], v[62:63], v[94:95], v[88:89] op_sel_hi:[1,1,0]
	v_pk_fma_f32 v[108:109], v[78:79], v[80:81], v[108:109]
	ds_read_b128 v[72:75], v115 offset:768
	ds_read_b128 v[76:79], v115 offset:784
	v_add_f32_e32 v110, v108, v109
	v_pk_fma_f32 v[82:83], v[56:57], v[104:105], v[88:89] op_sel_hi:[1,1,0]
	v_pk_fma_f32 v[80:81], v[58:59], v[106:107], v[88:89] op_sel_hi:[1,1,0]
	v_add_f32_dpp v110, v110, v110 quad_perm:[1,0,3,2] row_mask:0xf bank_mask:0xf bound_ctrl:1
	s_nop 1
	v_add_f32_dpp v110, v110, v110 quad_perm:[2,3,0,1] row_mask:0xf bank_mask:0xf bound_ctrl:1
	s_nop 1
	v_add_f32_dpp v110, v110, v110 row_half_mirror row_mask:0xf bank_mask:0xf bound_ctrl:1
	s_nop 0
	ds_write_b32 v112, v110 offset:256
	s_waitcnt lgkmcnt(3)
	ds_read_b128 v[60:63], v113 offset:1024
	ds_read_b128 v[56:59], v113 offset:1040
	ds_read_b32 v88, v114 offset:1024
	v_pk_mul_f32 v[108:109], v[52:53], v[86:87]
	v_pk_add_f32 v[92:93], v[86:87], v[90:91] op_sel_hi:[1,0] neg_lo:[0,1] neg_hi:[0,1]
	v_pk_add_f32 v[94:95], v[84:85], v[90:91] op_sel_hi:[1,0] neg_lo:[0,1] neg_hi:[0,1]
	v_pk_fma_f32 v[108:109], v[54:55], v[84:85], v[108:109]
	v_pk_add_f32 v[104:105], v[82:83], v[90:91] op_sel_hi:[1,0] neg_lo:[0,1] neg_hi:[0,1]
	v_pk_add_f32 v[106:107], v[80:81], v[90:91] op_sel_hi:[1,0] neg_lo:[0,1] neg_hi:[0,1]
	v_pk_fma_f32 v[108:109], v[48:49], v[82:83], v[108:109]
	v_pk_fma_f32 v[86:87], v[64:65], v[92:93], v[90:91] op_sel_hi:[1,1,0]
	v_pk_fma_f32 v[84:85], v[66:67], v[94:95], v[90:91] op_sel_hi:[1,1,0]
	v_pk_fma_f32 v[108:109], v[50:51], v[80:81], v[108:109]
	ds_read_b128 v[52:55], v115 offset:1024
	ds_read_b128 v[48:51], v115 offset:1040
	v_add_f32_e32 v110, v108, v109
	v_pk_fma_f32 v[82:83], v[68:69], v[104:105], v[90:91] op_sel_hi:[1,1,0]
	v_pk_fma_f32 v[80:81], v[70:71], v[106:107], v[90:91] op_sel_hi:[1,1,0]
	v_add_f32_dpp v110, v110, v110 quad_perm:[1,0,3,2] row_mask:0xf bank_mask:0xf bound_ctrl:1
	s_nop 1
	v_add_f32_dpp v110, v110, v110 quad_perm:[2,3,0,1] row_mask:0xf bank_mask:0xf bound_ctrl:1
	s_nop 1
	v_add_f32_dpp v110, v110, v110 row_half_mirror row_mask:0xf bank_mask:0xf bound_ctrl:1
	s_nop 0
	ds_write_b32 v112, v110 offset:512
	s_waitcnt lgkmcnt(3)
	ds_read_b128 v[64:67], v113 offset:1280
	ds_read_b128 v[68:71], v113 offset:1296
	ds_read_b32 v90, v114 offset:1280
	v_pk_mul_f32 v[108:109], v[72:73], v[86:87]
	v_pk_add_f32 v[92:93], v[86:87], v[88:89] op_sel_hi:[1,0] neg_lo:[0,1] neg_hi:[0,1]
	v_pk_add_f32 v[94:95], v[84:85], v[88:89] op_sel_hi:[1,0] neg_lo:[0,1] neg_hi:[0,1]
	v_pk_fma_f32 v[108:109], v[74:75], v[84:85], v[108:109]
	v_pk_add_f32 v[104:105], v[82:83], v[88:89] op_sel_hi:[1,0] neg_lo:[0,1] neg_hi:[0,1]
	v_pk_add_f32 v[106:107], v[80:81], v[88:89] op_sel_hi:[1,0] neg_lo:[0,1] neg_hi:[0,1]
	v_pk_fma_f32 v[108:109], v[76:77], v[82:83], v[108:109]
	v_pk_fma_f32 v[86:87], v[60:61], v[92:93], v[88:89] op_sel_hi:[1,1,0]
	v_pk_fma_f32 v[84:85], v[62:63], v[94:95], v[88:89] op_sel_hi:[1,1,0]
	v_pk_fma_f32 v[108:109], v[78:79], v[80:81], v[108:109]
	ds_read_b128 v[72:75], v115 offset:1280
	ds_read_b128 v[76:79], v115 offset:1296
	v_add_f32_e32 v110, v108, v109
	v_pk_fma_f32 v[82:83], v[56:57], v[104:105], v[88:89] op_sel_hi:[1,1,0]
	v_pk_fma_f32 v[80:81], v[58:59], v[106:107], v[88:89] op_sel_hi:[1,1,0]
	v_add_f32_dpp v110, v110, v110 quad_perm:[1,0,3,2] row_mask:0xf bank_mask:0xf bound_ctrl:1
	v_add_u32_e32 v113, 1024, v113
	v_add_u32_e32 v114, 1024, v114
	v_add_f32_dpp v110, v110, v110 quad_perm:[2,3,0,1] row_mask:0xf bank_mask:0xf bound_ctrl:1
	v_add_u32_e32 v115, 1024, v115
	s_nop 0
	v_add_f32_dpp v110, v110, v110 row_half_mirror row_mask:0xf bank_mask:0xf bound_ctrl:1
	s_nop 0
	ds_write_b32 v112, v110 offset:768
	v_add_u32_e32 v112, 1024, v112
	s_add_i32 s1, s1, 1
	s_cmp_lt_u32 s1, 32
	s_cbranch_scc1 .Lhg_loop
	s_waitcnt lgkmcnt(0)
	s_branch .LBB0_427
